# P0: layer-0 w_in conversion items dealt wave-major so every CU converts 3-4 tiles instead of 104 CUs converting 8
# speedup vs baseline: 1.0510x; 1.0030x over previous
; #define LAS __attribute__((address_space(3)))
; __device__ __forceinline__ void convert_layer_items(const float* const* in, unsigned char* ws, int l, int first, int stride, LAS float* scr, int lane, int mode) {
;     unsigned char* wl = ws + WS_W + (size_t)l * W_LAYER;
;     const int count = mode == 0 ? I_IN : (mode == 1 ? I_LAYER - I_IN : I_LAYER);
;     for (int it = first; it < count; it += stride) {
;         int r = mode == 0 ? it + I_P : (mode == 1 ? (it < I_P ? it : it + I_IN) : it);
; __global__ void __launch_bounds__(NWAVES * 64, 2) mk_fwd(Args args) {
;     ...
;     if (IN(0) && (DBG_MASK & 1)) {
;         LAS float* scr = (LAS float*)(lds + RING_OFF + wave * TR_SCR_BYTES);
;         convert_layer_items(args.in, ws, 0, gw, NGW, scr, lane, 0);
.LBB0_12:
	s_or_b64 exec, exec, s[4:5]
	v_readlane_b32 s4, v242, 22
	v_readlane_b32 s18, v242, 36
	v_readlane_b32 s19, v242, 37
	s_add_u32 s72, s18, 0x80000
	s_addc_u32 s73, s19, 0
	s_add_u32 s90, s18, 0x3800000
	v_readlane_b32 s4, v242, 5
	s_addc_u32 s91, s19, 0
	s_lshr_b32 s50, s33, 6
	s_lshl_b32 s4, s4, 3
	s_add_i32 s54, s4, s50
	s_lshl_b32 s55, s96, 3
	v_readlane_b32 s2, v242, 0
	v_readlane_b32 s10, v242, 28
	v_readlane_b32 s11, v242, 29
	v_readlane_b32 s3, v242, 1
	s_cmp_lt_i32 s2, 1
	v_readlane_b32 s5, v242, 23
	v_readlane_b32 s6, v242, 24
	s_cselect_b64 s[10:11], -1, 0
	s_cmp_gt_i32 s3, 0
	s_cselect_b64 s[4:5], -1, 0
	s_mul_i32 s6, s50, 0x4100
	s_and_b64 s[4:5], s[10:11], s[4:5]
	s_add_i32 s2, s6, 0
	v_readlane_b32 s7, v242, 25
	v_readlane_b32 s8, v242, 26
	v_readlane_b32 s9, v242, 27
	v_readlane_b32 s12, v242, 30
	v_readlane_b32 s13, v242, 31
	v_readlane_b32 s14, v242, 32
	v_readlane_b32 s15, v242, 33
	v_readlane_b32 s16, v242, 34
	v_readlane_b32 s17, v242, 35
	v_writelane_b32 v242, s2, 40
	s_add_u32 s2, s18, 0x200000
	s_addc_u32 s3, s19, 0
	v_writelane_b32 v242, s2, 41
	v_and_b32_e32 v194, 63, v0
	s_nop 0
	v_writelane_b32 v242, s3, 42
	s_nop 0
	v_readlane_b32 s12, v242, 6
	v_readlane_b32 s14, v242, 8
	v_readlane_b32 s15, v242, 9
	s_cmp_lg_u64 s[14:15], 0
	s_cselect_b64 s[2:3], -1, 0
	v_readlane_b32 s13, v242, 7
	v_readlane_b32 s16, v242, 10
	v_readlane_b32 s17, v242, 11
	v_readlane_b32 s18, v242, 12
	v_readlane_b32 s19, v242, 13
	v_readlane_b32 s20, v242, 14
	v_readlane_b32 s21, v242, 15
	v_readlane_b32 s22, v242, 16
	v_readlane_b32 s23, v242, 17
	v_readlane_b32 s24, v242, 18
	v_readlane_b32 s25, v242, 19
	v_readlane_b32 s26, v242, 20
	v_readlane_b32 s27, v242, 21
	v_writelane_b32 v242, s2, 43
	s_andn2_b64 vcc, exec, s[4:5]
	s_nop 0
	v_writelane_b32 v242, s3, 44
	s_cbranch_vccnz .LBB0_50
	v_readlane_b32 s100, v242, 5
	s_lshl_b32 s99, s50, 8
	s_nop 2
	s_add_i32 s100, s100, s99
	s_cmpk_gt_i32 s100, 0x33f
	s_cbranch_scc1 .LBB0_41
	v_and_b32_e32 v2, 15, v0
	v_lshrrev_b32_e32 v94, 3, v194
	v_and_b32_e32 v6, 7, v0
	v_lshlrev_b32_e32 v2, 4, v2
	v_readlane_b32 s2, v242, 40
	v_mul_u32_u24_e32 v3, 0x820, v6
	v_lshlrev_b32_e32 v7, 2, v94
	v_readlane_b32 s12, v242, 22
	v_add_u32_e32 v4, s2, v2
	v_add3_u32 v102, s2, v3, v7
	v_readlane_b32 s26, v242, 36
	v_readlane_b32 s2, v242, 41
	v_readlane_b32 s13, v242, 23
	v_readlane_b32 s16, v242, 26
	v_readlane_b32 s17, v242, 27
	v_readlane_b32 s18, v242, 28
	v_readlane_b32 s19, v242, 29
	v_readlane_b32 s20, v242, 30
	v_readlane_b32 s21, v242, 31
	v_readlane_b32 s22, v242, 32
	v_readlane_b32 s23, v242, 33
	v_readlane_b32 s24, v242, 34
	v_readlane_b32 s25, v242, 35
	v_readlane_b32 s27, v242, 37
	s_add_u32 s12, s26, 0x880000
	v_lshlrev_b32_e32 v74, 4, v6
	v_mov_b32_e32 v75, 0
	v_readlane_b32 s3, v242, 42
	s_addc_u32 s13, s27, 0
	v_readlane_b32 s16, v242, 6
	v_lshl_add_u64 v[76:77], s[2:3], 0, v[74:75]
	v_readlane_b32 s2, v242, 43
	v_lshrrev_b32_e32 v1, 4, v194
	v_mov_b32_e32 v3, v75
	v_readlane_b32 s20, v242, 10
	v_readlane_b32 s21, v242, 11
	v_readlane_b32 s4, v242, 5
	v_readlane_b32 s3, v242, 44
	v_mul_u32_u24_e32 v5, 0x104, v1
	v_readlane_b32 s15, v242, 25
	v_readlane_b32 s17, v242, 7
	v_readlane_b32 s18, v242, 8
	v_readlane_b32 s19, v242, 9
	v_readlane_b32 s22, v242, 12
	v_readlane_b32 s23, v242, 13
	v_readlane_b32 s24, v242, 14
	v_readlane_b32 s25, v242, 15
	v_readlane_b32 s26, v242, 16
	v_readlane_b32 s27, v242, 17
	v_readlane_b32 s28, v242, 18
	v_readlane_b32 s29, v242, 19
	v_readlane_b32 s30, v242, 20
	v_readlane_b32 s31, v242, 21
	v_lshl_add_u64 v[78:79], s[20:21], 0, v[2:3]
	v_lshlrev_b32_e32 v74, 5, v6
	s_lshl_b32 s4, s4, 9
	s_lshl_b32 s5, s50, 6
	v_cndmask_b32_e64 v2, 0, 1, s[2:3]
	v_or_b32_e32 v95, 8, v94
	v_or_b32_e32 v96, 16, v94
	v_or_b32_e32 v97, 24, v94
	v_or_b32_e32 v98, 32, v94
	v_or_b32_e32 v99, 40, v94
	v_or_b32_e32 v100, 48, v94
	v_or_b32_e32 v101, 56, v94
	v_lshl_add_u64 v[80:81], s[18:19], 0, v[74:75]
	s_add_i32 s22, s4, s5
	s_lshl_b32 s23, s96, 9
	s_mov_b32 s15, 0
	s_mov_b32 s24, 0x82000
	s_mov_b32 s25, 0x8f000
	s_mov_b32 s26, 0x9c000
	v_cmp_ne_u32_e64 s[6:7], 1, v2
	v_add_u32_e32 v103, v4, v5
	s_movk_i32 s27, 0xf700
	s_movk_i32 s28, 0x2000
	s_movk_i32 s29, 0x4000
	s_movk_i32 s30, 0x6000
	s_mov_b32 s31, 0x8000
	s_mov_b32 s34, 0xa000
	s_mov_b32 s35, 0xc000
	s_mov_b32 s36, 0xe000
	s_mov_b32 s37, 0xf000
	s_mov_b64 s[16:17], 0x10000
	s_mov_b32 s38, s100
	s_lshl_b32 s22, s38, 6
	v_readlane_b32 s14, v242, 24
	s_branch .LBB0_16
